# grid barrier: XCD leader bumps the per-XCD generation word before its own acquire invalidate (followers released earlier), on the full stack
# speedup vs baseline: 1.0031x; 1.0031x over previous
; DI unsigned xb_ld(unsigned* p)              { return __hip_atomic_load(p, __ATOMIC_RELAXED, __HIP_MEMORY_SCOPE_AGENT); }
; DI unsigned xb_add(unsigned* p, unsigned v) { return __hip_atomic_fetch_add(p, v, __ATOMIC_RELAXED, __HIP_MEMORY_SCOPE_AGENT); }
; #define XB_SPIN(cond, bar) do { unsigned _sp = 0; while (cond) { __builtin_amdgcn_s_sleep(1); \
;     if ((++_sp & 255u) == 0u) { if (xb_ld(&(bar)[XB_TMO])) break; if (_sp > XB_SPIN_CAP) { atomicAdd(&(bar)[XB_TMO], 1u); break; } } } } while (0)
; DI void xcd_barrier(unsigned* bar, volatile LAS unsigned* st) {
;     ...
;         const unsigned old = xb_add(&bar[XB_XSUB(x)], 1u);
;         const unsigned gen = old / nloc;
;         if (old + 1u == (gen + 1u) * nloc) {
;             __builtin_amdgcn_fence(__ATOMIC_RELEASE, "agent");
;             asm volatile("s_waitcnt vmcnt(0)" ::: "memory");
;             const unsigned og = xb_add(&bar[XB_TOP], 1u);
;             const unsigned tg = og / nx;
;             if (og + 1u == (tg + 1u) * nx) xb_add(&bar[XB_TOPGEN], 1u);
;             else XB_SPIN(xb_ld(&bar[XB_TOPGEN]) == tg, bar);
;             __builtin_amdgcn_fence(__ATOMIC_ACQUIRE, "agent");
;             xb_add(&bar[XB_XGEN(x)], 1u);
;             asm volatile("s_waitcnt vmcnt(0)" ::: "memory");
;         } else {
;             XB_SPIN(xb_ld(&bar[XB_XGEN(x)]) == gen, bar);
;             __builtin_amdgcn_fence(__ATOMIC_ACQUIRE, "agent");
;             asm volatile("s_waitcnt vmcnt(0)" ::: "memory");
.LBB0_890:
	s_or_b64 exec, exec, s[8:9]
	s_mov_b64 s[8:9], exec
	v_mbcnt_lo_u32_b32 v0, s8, 0
	v_mbcnt_hi_u32_b32 v0, s9, v0
	v_cmp_eq_u32_e32 vcc, 0, v0
	s_waitcnt vmcnt(0)
	s_and_saveexec_b64 s[12:13], vcc
	s_cbranch_execz .LBB0_892
	s_bcnt1_i32_b64 s0, s[8:9]
	v_mov_b32_e32 v0, s0
	global_atomic_add v236, v0, s[10:11] offset:1024
.LBB0_892:
	s_or_b64 exec, exec, s[12:13]
	buffer_inv sc1
	s_waitcnt vmcnt(0)
